# P1 (adaLN RMSNorm) row loop: next row's loads issued before the current row is reduced (one row ahead, counted wait)
# baseline (speedup 1.0000x reference)
; __device__ void phase1(LAS unsigned char* lds, const Params& p) {
;     ...
;     int curj = -1;
;     for (int g = g0; g < g1; ++g) {
;         const int row0 = g * 8; const int j = row0 < NLAT ? (row0 >> 12) : 8;
;         if (j != curj) {
;             __syncthreads();
;             for (int i = tid; i < 1024; i += NTHR) { float sh = p.b_mod[i], sc = p.b_mod[1024 + i];
; #pragma unroll
;                 for (int q = 0; q < 4; ++q) { sh += modp[(q * 9 + j) * 3072 + i]; sc += modp[(q * 9 + j) * 3072 + 1024 + i]; }
;                 mv[i] = p.norm_g[i] * (1.f + sc); mv[1024 + i] = sh; }
;             __syncthreads(); curj = j;
;         }
;         const int row = row0 + w;
;         const float* xr = row < NLAT ? p.x + (size_t)row * 1024 : p.ctx + (size_t)(row - NLAT) * 1024;
;         f32x4 v[4]; float ss = 0.f;
; #pragma unroll
;         for (int c = 0; c < 4; ++c) { v[c] = *(const f32x4*)(xr + c * 256 + lane * 4); ss += v[c][0] * v[c][0] + v[c][1] * v[c][1] + v[c][2] * v[c][2] + v[c][3] * v[c][3]; }
.LBB0_91:
	s_cmp_ge_i32 s8, s10
	s_cbranch_scc1 .LBB0_102
	v_mbcnt_lo_u32_b32 v2, -1, 0
	v_mbcnt_hi_u32_b32 v2, -1, v2
	v_and_b32_e32 v4, 64, v2
	v_add_u32_e32 v4, 64, v4
	v_xor_b32_e32 v5, 32, v2
	v_cmp_lt_i32_e32 vcc, v5, v4
	v_lshlrev_b32_e32 v8, 2, v0
	v_and_b32_e32 v10, 0xfc, v8
	v_cndmask_b32_e32 v5, v2, v5, vcc
	v_lshlrev_b32_e32 v15, 2, v5
	v_xor_b32_e32 v5, 16, v2
	v_cmp_lt_i32_e32 vcc, v5, v4
	v_mov_b32_e32 v3, 0
	s_mov_b64 s[14:15], 0xd00000
	v_cndmask_b32_e32 v5, v2, v5, vcc
	v_lshlrev_b32_e32 v16, 2, v5
	v_xor_b32_e32 v5, 8, v2
	v_cmp_lt_i32_e32 vcc, v5, v4
	v_mov_b32_e32 v9, v3
	s_add_u32 s12, s70, 0xa00000
	v_cndmask_b32_e32 v5, v2, v5, vcc
	v_lshlrev_b32_e32 v17, 2, v5
	v_xor_b32_e32 v5, 4, v2
	v_cmp_lt_i32_e32 vcc, v5, v4
	v_lshl_add_u64 v[6:7], s[48:49], 0, v[8:9]
	v_lshrrev_b32_e32 v1, 6, v0
	v_cndmask_b32_e32 v5, v2, v5, vcc
	v_lshlrev_b32_e32 v18, 2, v5
	v_xor_b32_e32 v5, 2, v2
	v_cmp_lt_i32_e32 vcc, v5, v4
	s_addc_u32 s13, s71, 0
	s_mov_b32 s11, -1
	v_cndmask_b32_e32 v5, v2, v5, vcc
	v_lshlrev_b32_e32 v19, 2, v5
	v_xor_b32_e32 v5, 1, v2
	v_cmp_lt_i32_e32 vcc, v5, v4
	v_lshl_add_u32 v14, v10, 2, 0
	v_or_b32_e32 v21, 0xfffffe00, v0
	v_cndmask_b32_e32 v2, v2, v5, vcc
	v_lshlrev_b32_e32 v20, 2, v2
	v_lshlrev_b32_e32 v2, 1, v10
	v_lshl_add_u64 v[4:5], s[70:71], 0, v[2:3]
	v_lshl_add_u64 v[4:5], v[4:5], 0, s[14:15]
	s_mov_b64 s[14:15], 0x1000
	v_add_u32_e32 v22, 0, v8
	v_lshl_add_u64 v[6:7], v[6:7], 0, s[14:15]
	v_lshl_add_u64 v[8:9], s[44:45], 0, v[8:9]
	s_mov_b64 s[14:15], 0x800
	s_movk_i32 s3, 0x7fff
	v_lshlrev_b32_e32 v2, 2, v10
	v_mov_b32_e32 v23, 0x358637bd
	s_mov_b32 s9, 0x800000
	s_mov_b32 s20, s8
	v_lshl_or_b32 v70, s20, 3, v1
	v_cmp_lt_i32_e32 vcc, s3, v70
	v_add_u32_e32 v72, 0xffff8000, v70
	v_cndmask_b32_e32 v72, v70, v72, vcc
	v_mov_b32_e32 v73, 0
	v_lshlrev_b64 v[72:73], 12, v[72:73]
	v_mov_b32_e32 v74, s36
	v_mov_b32_e32 v75, s37
	v_mov_b32_e32 v76, s40
	v_mov_b32_e32 v77, s41
	v_cndmask_b32_e32 v74, v74, v76, vcc
	v_cndmask_b32_e32 v75, v75, v77, vcc
	v_lshl_add_u64 v[72:73], v[74:75], 0, v[72:73]
	v_lshl_add_u64 v[72:73], v[72:73], 0, v[2:3]
	global_load_dwordx4 v[54:57], v[72:73], off
	global_load_dwordx4 v[58:61], v[72:73], off offset:1024
	global_load_dwordx4 v[62:65], v[72:73], off offset:2048
	global_load_dwordx4 v[66:69], v[72:73], off offset:3072
	s_branch .LBB0_94
; #define LAS __attribute__((address_space(3)))
; __device__ __forceinline__ unsigned cvt_pk_bf16(float lo, float hi) { unsigned r; asm volatile("v_cvt_pk_bf16_f32 %0, %1, %2" : "=v"(r) : "v"(lo), "v"(hi)); return r; }
; __device__ void phase1(LAS unsigned char* lds, const Params& p) {
;     ...
;         const int row = row0 + w;
;         const float* xr = row < NLAT ? p.x + (size_t)row * 1024 : p.ctx + (size_t)(row - NLAT) * 1024;
;         f32x4 v[4]; float ss = 0.f;
; #pragma unroll
;         for (int c = 0; c < 4; ++c) { v[c] = *(const f32x4*)(xr + c * 256 + lane * 4); ss += v[c][0] * v[c][0] + v[c][1] * v[c][1] + v[c][2] * v[c][2] + v[c][3] * v[c][3]; }
; #pragma unroll
;         for (int m = 32; m >= 1; m >>= 1) ss += __shfl_xor(ss, m);
;         const float rs = rsqrtf(ss * (1.f / 1024.f) + EPS);
; #pragma unroll
;         for (int c = 0; c < 4; ++c) { const int k = c * 256 + lane * 4; const f32x4 m0 = *(const LAS f32x4*)(mv + k), m1 = *(const LAS f32x4*)(mv + 1024 + k);
;             const f32x4 a = v[c] * rs * m0 + m1; u32x2 o = {cvt_pk_bf16(a[0], a[1]), cvt_pk_bf16(a[2], a[3])}; *(u32x2*)(A + (size_t)row * 1024 + k) = o; }
.LBB0_93:
	s_or_b64 exec, exec, s[16:17]
	s_waitcnt vmcnt(4)
	v_mov_b32_e32 v24, v54
	v_mov_b32_e32 v25, v55
	v_mov_b32_e32 v26, v56
	v_mov_b32_e32 v27, v57
	v_mov_b32_e32 v28, v58
	v_mov_b32_e32 v29, v59
	v_mov_b32_e32 v30, v60
	v_mov_b32_e32 v31, v61
	v_mov_b32_e32 v32, v62
	v_mov_b32_e32 v33, v63
	v_mov_b32_e32 v34, v64
	v_mov_b32_e32 v35, v65
	v_mov_b32_e32 v36, v66
	v_mov_b32_e32 v37, v67
	v_mov_b32_e32 v38, v68
	v_mov_b32_e32 v39, v69
	s_add_i32 s20, s8, 1
	s_sub_i32 s21, s10, 1
	s_min_i32 s20, s20, s21
	v_lshl_or_b32 v70, s20, 3, v1
	v_cmp_lt_i32_e32 vcc, s3, v70
	v_add_u32_e32 v72, 0xffff8000, v70
	v_cndmask_b32_e32 v72, v70, v72, vcc
	v_mov_b32_e32 v73, 0
	v_lshlrev_b64 v[72:73], 12, v[72:73]
	v_mov_b32_e32 v74, s36
	v_mov_b32_e32 v75, s37
	v_mov_b32_e32 v76, s40
	v_mov_b32_e32 v77, s41
	v_cndmask_b32_e32 v74, v74, v76, vcc
	v_cndmask_b32_e32 v75, v75, v77, vcc
	v_lshl_add_u64 v[72:73], v[74:75], 0, v[72:73]
	v_lshl_add_u64 v[72:73], v[72:73], 0, v[2:3]
	global_load_dwordx4 v[54:57], v[72:73], off
	global_load_dwordx4 v[58:61], v[72:73], off offset:1024
	global_load_dwordx4 v[62:65], v[72:73], off offset:2048
	global_load_dwordx4 v[66:69], v[72:73], off offset:3072
	s_add_i32 s8, s8, 1
	s_cmp_lt_i32 s8, s10
	v_mov_b32_e32 v40, v25
	v_mov_b32_e32 v41, v29
	v_mov_b32_e32 v12, v24
	v_mov_b32_e32 v13, v28
	v_mov_b32_e32 v48, v33
	v_mov_b32_e32 v49, v37
	v_pk_mul_f32 v[40:41], v[40:41], v[40:41]
	v_mov_b32_e32 v42, v26
	v_mov_b32_e32 v43, v30
	v_mov_b32_e32 v46, v32
	v_mov_b32_e32 v47, v36
	v_pk_mul_f32 v[48:49], v[48:49], v[48:49]
	v_pk_fma_f32 v[12:13], v[12:13], v[12:13], v[40:41]
	v_mov_b32_e32 v44, v27
	v_mov_b32_e32 v45, v31
	v_mov_b32_e32 v50, v34
	v_mov_b32_e32 v51, v38
	v_pk_fma_f32 v[40:41], v[46:47], v[46:47], v[48:49]
	v_pk_fma_f32 v[12:13], v[42:43], v[42:43], v[12:13]
	v_mov_b32_e32 v52, v35
	v_mov_b32_e32 v53, v39
	v_pk_fma_f32 v[40:41], v[50:51], v[50:51], v[40:41]
	v_pk_fma_f32 v[12:13], v[44:45], v[44:45], v[12:13]
	v_pk_fma_f32 v[40:41], v[52:53], v[52:53], v[40:41]
	v_add_f32_e32 v12, v12, v13
	v_add_f32_e32 v12, v12, v40
	v_add_f32_e32 v12, v12, v41
	ds_bpermute_b32 v13, v15, v12
	v_lshlrev_b64 v[44:45], 11, v[10:11]
	s_waitcnt lgkmcnt(0)
	v_add_f32_e32 v12, v12, v13
	ds_bpermute_b32 v13, v16, v12
	s_waitcnt lgkmcnt(0)
	v_add_f32_e32 v12, v12, v13
	ds_bpermute_b32 v13, v17, v12
	s_waitcnt lgkmcnt(0)
	v_add_f32_e32 v12, v12, v13
	ds_bpermute_b32 v13, v18, v12
	s_waitcnt lgkmcnt(0)
	v_add_f32_e32 v12, v12, v13
	ds_bpermute_b32 v13, v19, v12
	s_waitcnt lgkmcnt(0)
	v_add_f32_e32 v12, v12, v13
	ds_bpermute_b32 v13, v20, v12
	s_waitcnt lgkmcnt(0)
	v_add_f32_e32 v12, v12, v13
	v_fmamk_f32 v12, v12, 0x3a800000, v23
	v_mul_f32_e32 v13, 0x4b800000, v12
	v_cmp_gt_f32_e32 vcc, s9, v12
	s_nop 1
	v_cndmask_b32_e32 v12, v12, v13, vcc
	v_rsq_f32_e32 v46, v12
	ds_read_b128 v[10:13], v14
	ds_read_b128 v[40:43], v14 offset:4096
	v_mul_f32_e32 v47, 0x45800000, v46
	v_cndmask_b32_e32 v46, v46, v47, vcc
	v_pk_mul_f32 v[24:25], v[24:25], v[46:47] op_sel_hi:[1,0]
	v_pk_mul_f32 v[26:27], v[26:27], v[46:47] op_sel_hi:[1,0]
	s_waitcnt lgkmcnt(0)
	v_pk_fma_f32 v[10:11], v[10:11], v[24:25], v[40:41]
	v_pk_fma_f32 v[12:13], v[12:13], v[26:27], v[42:43]
	v_cvt_pk_bf16_f32 v40, v10, v11
	v_pk_mul_f32 v[28:29], v[28:29], v[46:47] op_sel_hi:[1,0]
	v_cvt_pk_bf16_f32 v41, v12, v13
	ds_read_b128 v[10:13], v14 offset:1024
	ds_read_b128 v[24:27], v14 offset:5120
	v_pk_mul_f32 v[30:31], v[30:31], v[46:47] op_sel_hi:[1,0]
	v_lshl_add_u64 v[42:43], v[4:5], 0, v[44:45]
	global_store_dwordx2 v[42:43], v[40:41], off
	s_waitcnt lgkmcnt(0)
	v_pk_fma_f32 v[12:13], v[12:13], v[30:31], v[26:27]
	v_pk_fma_f32 v[10:11], v[10:11], v[28:29], v[24:25]
	v_pk_mul_f32 v[30:31], v[32:33], v[46:47] op_sel_hi:[1,0]
	v_cvt_pk_bf16_f32 v28, v10, v11
	v_cvt_pk_bf16_f32 v29, v12, v13
	ds_read_b128 v[10:13], v14 offset:2048
	ds_read_b128 v[24:27], v14 offset:6144
	v_pk_mul_f32 v[32:33], v[34:35], v[46:47] op_sel_hi:[1,0]
	global_store_dwordx2 v[42:43], v[28:29], off offset:512
	s_waitcnt lgkmcnt(0)
	v_pk_fma_f32 v[12:13], v[12:13], v[32:33], v[26:27]
	v_pk_fma_f32 v[10:11], v[10:11], v[30:31], v[24:25]
	v_pk_mul_f32 v[30:31], v[36:37], v[46:47] op_sel_hi:[1,0]
	v_cvt_pk_bf16_f32 v28, v10, v11
	v_cvt_pk_bf16_f32 v29, v12, v13
	ds_read_b128 v[10:13], v14 offset:3072
	ds_read_b128 v[24:27], v14 offset:7168
	v_pk_mul_f32 v[32:33], v[38:39], v[46:47] op_sel_hi:[1,0]
	global_store_dwordx2 v[42:43], v[28:29], off offset:1024
	s_waitcnt lgkmcnt(0)
	v_pk_fma_f32 v[10:11], v[10:11], v[30:31], v[24:25]
	v_pk_fma_f32 v[12:13], v[12:13], v[32:33], v[26:27]
	v_cvt_pk_bf16_f32 v10, v10, v11
	s_nop 0
	v_cvt_pk_bf16_f32 v11, v12, v13
	global_store_dwordx2 v[42:43], v[10:11], off offset:1536
	s_cbranch_scc0 .LBB0_102
